# v16 + windowed loops: partially-masked tiles use a hand-written 6-instruction-per-row mask (unsigned range compare, two mask registers) instead of the compiler's select chain
# speedup vs baseline: 1.0229x; 1.0036x over previous
; template <int DQK, bool WIN>
; DI void attn_run(int wv, const bf16_t* Qrow0, int qs, const bf16_t* Kb, int ks, const bf16_t* Vb, int vs,
;                  int kt0, int kt1, int qpos0, int window, LAS unsigned char* lds, f32x16 (&o)[2], float& m_out, float& l_out) {
;     ...
;             if (WIN) {
;                 const int qp_ = qpos0 + r32, kb_ = 64 * kt + 4 * h;
; #pragma unroll
;                 for (int r = 0; r < 16; ++r) {
;                     const int kk = kb_ + (r & 3) + 8 * (r >> 2);
;                     int d0 = qp_ - kk; d0 = d0 < 0 ? -d0 : d0;
;                     int d1 = qp_ - kk - 32; d1 = d1 < 0 ? -d1 : d1;
;                     if (d0 > window) p0[r] = -1e30f;
;                     if (d1 > window) p1[r] = -1e30f;
;                 }
;             }
.Lwd_slow:
	s_movk_i32 m0, 129
	v_add_u32_e32 v218, 0x40, v159
	v_add_u32_e32 v219, 0xffffffe0, v218
	v_cmp_gt_u32_e32 vcc, m0, v218
	v_cmp_gt_u32_e64 s[98:99], m0, v219
	v_add_u32_e32 v220, 0x3f, v159
	v_add_u32_e32 v221, 0xffffffe0, v220
	s_nop 3
	v_cndmask_b32_e32 v142, v203, v64, vcc
	v_cndmask_b32_e64 v64, v203, v48, s[98:99]
	v_cmp_gt_u32_e32 vcc, m0, v220
	v_cmp_gt_u32_e64 s[98:99], m0, v221
	v_add_u32_e32 v218, 0x3e, v159
	v_add_u32_e32 v219, 0xffffffe0, v218
	v_cndmask_b32_e32 v143, v203, v65, vcc
	v_cndmask_b32_e64 v65, v203, v49, s[98:99]
	v_cmp_gt_u32_e32 vcc, m0, v218
	v_cmp_gt_u32_e64 s[98:99], m0, v219
	v_add_u32_e32 v220, 0x3d, v159
	v_add_u32_e32 v221, 0xffffffe0, v220
	v_cndmask_b32_e32 v146, v203, v66, vcc
	v_cndmask_b32_e64 v66, v203, v50, s[98:99]
	v_cmp_gt_u32_e32 vcc, m0, v220
	v_cmp_gt_u32_e64 s[98:99], m0, v221
	v_add_u32_e32 v218, 0x38, v159
	v_add_u32_e32 v219, 0xffffffe0, v218
	v_cndmask_b32_e32 v147, v203, v67, vcc
	v_cndmask_b32_e64 v67, v203, v51, s[98:99]
	v_cmp_gt_u32_e32 vcc, m0, v218
	v_cmp_gt_u32_e64 s[98:99], m0, v219
	v_add_u32_e32 v220, 0x37, v159
	v_add_u32_e32 v221, 0xffffffe0, v220
	v_cndmask_b32_e32 v148, v203, v68, vcc
	v_cndmask_b32_e64 v68, v203, v52, s[98:99]
	v_cmp_gt_u32_e32 vcc, m0, v220
	v_cmp_gt_u32_e64 s[98:99], m0, v221
	v_add_u32_e32 v218, 0x36, v159
	v_add_u32_e32 v219, 0xffffffe0, v218
	v_cndmask_b32_e32 v149, v203, v69, vcc
	v_cndmask_b32_e64 v69, v203, v53, s[98:99]
	v_cmp_gt_u32_e32 vcc, m0, v218
	v_cmp_gt_u32_e64 s[98:99], m0, v219
	v_add_u32_e32 v220, 0x35, v159
	v_add_u32_e32 v221, 0xffffffe0, v220
	v_cndmask_b32_e32 v150, v203, v70, vcc
	v_cndmask_b32_e64 v70, v203, v54, s[98:99]
	v_cmp_gt_u32_e32 vcc, m0, v220
	v_cmp_gt_u32_e64 s[98:99], m0, v221
	v_add_u32_e32 v218, 0x30, v159
	v_add_u32_e32 v219, 0xffffffe0, v218
	v_cndmask_b32_e32 v151, v203, v71, vcc
	v_cndmask_b32_e64 v71, v203, v55, s[98:99]
	v_cmp_gt_u32_e32 vcc, m0, v218
	v_cmp_gt_u32_e64 s[98:99], m0, v219
	v_add_u32_e32 v220, 0x2f, v159
	v_add_u32_e32 v221, 0xffffffe0, v220
	v_cndmask_b32_e32 v72, v203, v72, vcc
	v_cndmask_b32_e64 v56, v203, v56, s[98:99]
	v_cmp_gt_u32_e32 vcc, m0, v220
	v_cmp_gt_u32_e64 s[98:99], m0, v221
	v_add_u32_e32 v218, 0x2e, v159
	v_add_u32_e32 v219, 0xffffffe0, v218
	v_cndmask_b32_e32 v73, v203, v73, vcc
	v_cndmask_b32_e64 v57, v203, v57, s[98:99]
	v_cmp_gt_u32_e32 vcc, m0, v218
	v_cmp_gt_u32_e64 s[98:99], m0, v219
	v_add_u32_e32 v220, 0x2d, v159
	v_add_u32_e32 v221, 0xffffffe0, v220
	v_cndmask_b32_e32 v74, v203, v74, vcc
	v_cndmask_b32_e64 v58, v203, v58, s[98:99]
	v_cmp_gt_u32_e32 vcc, m0, v220
	v_cmp_gt_u32_e64 s[98:99], m0, v221
	v_add_u32_e32 v218, 0x28, v159
	v_add_u32_e32 v219, 0xffffffe0, v218
	v_cndmask_b32_e32 v75, v203, v75, vcc
	v_cndmask_b32_e64 v59, v203, v59, s[98:99]
	v_cmp_gt_u32_e32 vcc, m0, v218
	v_cmp_gt_u32_e64 s[98:99], m0, v219
	v_add_u32_e32 v220, 0x27, v159
	v_add_u32_e32 v221, 0xffffffe0, v220
	v_cndmask_b32_e32 v76, v203, v76, vcc
	v_cndmask_b32_e64 v60, v203, v60, s[98:99]
	v_cmp_gt_u32_e32 vcc, m0, v220
	v_cmp_gt_u32_e64 s[98:99], m0, v221
	v_add_u32_e32 v218, 0x26, v159
	v_add_u32_e32 v219, 0xffffffe0, v218
	v_cndmask_b32_e32 v77, v203, v77, vcc
	v_cndmask_b32_e64 v61, v203, v61, s[98:99]
	v_cmp_gt_u32_e32 vcc, m0, v218
	v_cmp_gt_u32_e64 s[98:99], m0, v219
	v_add_u32_e32 v220, 0x25, v159
	v_add_u32_e32 v221, 0xffffffe0, v220
	v_cndmask_b32_e32 v78, v203, v78, vcc
	v_cndmask_b32_e64 v62, v203, v62, s[98:99]
	v_cmp_gt_u32_e32 vcc, m0, v220
	v_cmp_gt_u32_e64 s[98:99], m0, v221
	s_nop 1
	v_cndmask_b32_e32 v79, v203, v79, vcc
	v_cndmask_b32_e64 v63, v203, v63, s[98:99]

; template <int DQK, bool WIN>
; DI void attn_run(int wv, const bf16_t* Qrow0, int qs, const bf16_t* Kb, int ks, const bf16_t* Vb, int vs,
;                  int kt0, int kt1, int qpos0, int window, LAS unsigned char* lds, f32x16 (&o)[2], float& m_out, float& l_out) {
;     ...
;             if (WIN) {
;                 const int qp_ = qpos0 + r32, kb_ = 64 * kt + 4 * h;
; #pragma unroll
;                 for (int r = 0; r < 16; ++r) {
;                     const int kk = kb_ + (r & 3) + 8 * (r >> 2);
;                     int d0 = qp_ - kk; d0 = d0 < 0 ? -d0 : d0;
;                     int d1 = qp_ - kk - 32; d1 = d1 < 0 ? -d1 : d1;
;                     if (d0 > window) p0[r] = -1e30f;
;                     if (d1 > window) p1[r] = -1e30f;
;                 }
;             }
.Lwc_slow:
	s_movk_i32 m0, 257
	v_add_u32_e32 v218, 0x9b, v159
	v_add_u32_e32 v219, 0xffffffe0, v218
	v_cmp_gt_u32_e32 vcc, m0, v218
	v_cmp_gt_u32_e64 s[98:99], m0, v219
	v_add_u32_e32 v220, 0x9a, v159
	v_add_u32_e32 v221, 0xffffffe0, v220
	s_nop 3
	v_cndmask_b32_e32 v142, v203, v64, vcc
	v_cndmask_b32_e64 v64, v203, v48, s[98:99]
	v_cmp_gt_u32_e32 vcc, m0, v220
	v_cmp_gt_u32_e64 s[98:99], m0, v221
	v_add_u32_e32 v218, 0x99, v159
	v_add_u32_e32 v219, 0xffffffe0, v218
	v_cndmask_b32_e32 v143, v203, v65, vcc
	v_cndmask_b32_e64 v65, v203, v49, s[98:99]
	v_cmp_gt_u32_e32 vcc, m0, v218
	v_cmp_gt_u32_e64 s[98:99], m0, v219
	v_add_u32_e32 v220, 0x98, v159
	v_add_u32_e32 v221, 0xffffffe0, v220
	v_cndmask_b32_e32 v146, v203, v66, vcc
	v_cndmask_b32_e64 v66, v203, v50, s[98:99]
	v_cmp_gt_u32_e32 vcc, m0, v220
	v_cmp_gt_u32_e64 s[98:99], m0, v221
	v_add_u32_e32 v218, 0x93, v159
	v_add_u32_e32 v219, 0xffffffe0, v218
	v_cndmask_b32_e32 v147, v203, v67, vcc
	v_cndmask_b32_e64 v67, v203, v51, s[98:99]
	v_cmp_gt_u32_e32 vcc, m0, v218
	v_cmp_gt_u32_e64 s[98:99], m0, v219
	v_add_u32_e32 v220, 0x92, v159
	v_add_u32_e32 v221, 0xffffffe0, v220
	v_cndmask_b32_e32 v148, v203, v68, vcc
	v_cndmask_b32_e64 v68, v203, v52, s[98:99]
	v_cmp_gt_u32_e32 vcc, m0, v220
	v_cmp_gt_u32_e64 s[98:99], m0, v221
	v_add_u32_e32 v218, 0x91, v159
	v_add_u32_e32 v219, 0xffffffe0, v218
	v_cndmask_b32_e32 v149, v203, v69, vcc
	v_cndmask_b32_e64 v69, v203, v53, s[98:99]
	v_cmp_gt_u32_e32 vcc, m0, v218
	v_cmp_gt_u32_e64 s[98:99], m0, v219
	v_add_u32_e32 v220, 0x90, v159
	v_add_u32_e32 v221, 0xffffffe0, v220
	v_cndmask_b32_e32 v150, v203, v70, vcc
	v_cndmask_b32_e64 v70, v203, v54, s[98:99]
	v_cmp_gt_u32_e32 vcc, m0, v220
	v_cmp_gt_u32_e64 s[98:99], m0, v221
	v_add_u32_e32 v218, 0x8b, v159
	v_add_u32_e32 v219, 0xffffffe0, v218
	v_cndmask_b32_e32 v151, v203, v71, vcc
	v_cndmask_b32_e64 v71, v203, v55, s[98:99]
	v_cmp_gt_u32_e32 vcc, m0, v218
	v_cmp_gt_u32_e64 s[98:99], m0, v219
	v_add_u32_e32 v220, 0x8a, v159
	v_add_u32_e32 v221, 0xffffffe0, v220
	v_cndmask_b32_e32 v72, v203, v72, vcc
	v_cndmask_b32_e64 v56, v203, v56, s[98:99]
	v_cmp_gt_u32_e32 vcc, m0, v220
	v_cmp_gt_u32_e64 s[98:99], m0, v221
	v_add_u32_e32 v218, 0x89, v159
	v_add_u32_e32 v219, 0xffffffe0, v218
	v_cndmask_b32_e32 v73, v203, v73, vcc
	v_cndmask_b32_e64 v57, v203, v57, s[98:99]
	v_cmp_gt_u32_e32 vcc, m0, v218
	v_cmp_gt_u32_e64 s[98:99], m0, v219
	v_add_u32_e32 v220, 0x88, v159
	v_add_u32_e32 v221, 0xffffffe0, v220
	v_cndmask_b32_e32 v74, v203, v74, vcc
	v_cndmask_b32_e64 v58, v203, v58, s[98:99]
	v_cmp_gt_u32_e32 vcc, m0, v220
	v_cmp_gt_u32_e64 s[98:99], m0, v221
	v_add_u32_e32 v218, 0x83, v159
	v_add_u32_e32 v219, 0xffffffe0, v218
	v_cndmask_b32_e32 v75, v203, v75, vcc
	v_cndmask_b32_e64 v59, v203, v59, s[98:99]
	v_cmp_gt_u32_e32 vcc, m0, v218
	v_cmp_gt_u32_e64 s[98:99], m0, v219
	v_add_u32_e32 v220, 0x82, v159
	v_add_u32_e32 v221, 0xffffffe0, v220
	v_cndmask_b32_e32 v76, v203, v76, vcc
	v_cndmask_b32_e64 v60, v203, v60, s[98:99]
	v_cmp_gt_u32_e32 vcc, m0, v220
	v_cmp_gt_u32_e64 s[98:99], m0, v221
	v_add_u32_e32 v218, 0x81, v159
	v_add_u32_e32 v219, 0xffffffe0, v218
	v_cndmask_b32_e32 v77, v203, v77, vcc
	v_cndmask_b32_e64 v61, v203, v61, s[98:99]
	v_cmp_gt_u32_e32 vcc, m0, v218
	v_cmp_gt_u32_e64 s[98:99], m0, v219
	v_add_u32_e32 v220, 0x80, v159
	v_add_u32_e32 v221, 0xffffffe0, v220
	v_cndmask_b32_e32 v78, v203, v78, vcc
	v_cndmask_b32_e64 v62, v203, v62, s[98:99]
	v_cmp_gt_u32_e32 vcc, m0, v220
	v_cmp_gt_u32_e64 s[98:99], m0, v221
	s_nop 1
	v_cndmask_b32_e32 v79, v203, v79, vcc
	v_cndmask_b32_e64 v63, v203, v63, s[98:99]
